# P3 sample-row tasks all on the loader waves (head from task id), which start them during the scan's last chunk: last-iteration and post-scan workgroup barriers skipped
# speedup vs baseline: 1.0190x; 1.0054x over previous
; __device__ __forceinline__ void rwkv_scan_prompt(const Params& p, LAS unsigned char* lds, int bh, int rq) {
;     ...
;     __syncthreads();
; __device__ __forceinline__ void p3_scan(const Params& p, LAS unsigned char* lds) {
;     for (int j = blockIdx.x; j < 256; j += gridDim.x) {
;         const int xcd = j & 7, slot = j >> 3;
;         rwkv_scan_prompt(p, lds, xcd * 8 + (slot >> 2), slot & 3);
;     }
.LBB0_310:
	s_or_b64 exec, exec, s[58:59]
	s_add_i32 s3, s3, s33
	s_add_i32 s93, s93, s88
	s_cmpk_gt_i32 s3, 0xff
	s_waitcnt lgkmcnt(0)
	s_cbranch_scc1 .LBB0_360
	s_barrier

; __device__ __forceinline__ void rwkv_scan_prompt(const Params& p, LAS unsigned char* lds, int bh, int rq) {
;     ...
;     for (int c = 0; c < NCH; ++c) {
;         const int buf = c & 1;
;         if (wave >= 4) {
;             if (c + 1 < NCH) store_chunk(buf ^ 1);
;             if (c + 2 < NCH) issue_chunk(c + 2);
;         } else {
;             float yk[TC / 16];
; #pragma unroll
;             for (int j = 0; j < TC / 16; ++j) yk[j] = 0.f;
;             const LAS float* ob = OPS + buf * TC * 6 * 64;
;             f32x4 r4 = *(const LAS f32x4*)(ob + cg_ * 4), d4 = *(const LAS f32x4*)(ob + 64 + cg_ * 4), k4 = *(const LAS f32x4*)(ob + 128 + cg_ * 4),
;                   a4 = *(const LAS f32x4*)(ob + 256 + cg_ * 4), b4 = *(const LAS f32x4*)(ob + 320 + cg_ * 4);
;             float vv = ob[192 + rq * 16 + rloc];
;             f32x4 rp = r4;
; #pragma unroll
;             for (int tk = 0; tk < TC; ++tk) {
;                 f32x4 nr4 = r4, nd4 = d4, nk4 = k4, na4 = a4, nb4 = b4; float nvv = vv;
;                 if (tk < TC - 1) {
;                     const LAS float* o = ob + (tk + 1) * 6 * 64;
;                     nr4 = *(const LAS f32x4*)(o + cg_ * 4); nd4 = *(const LAS f32x4*)(o + 64 + cg_ * 4); nk4 = *(const LAS f32x4*)(o + 128 + cg_ * 4);
;                     na4 = *(const LAS f32x4*)(o + 256 + cg_ * 4); nb4 = *(const LAS f32x4*)(o + 320 + cg_ * 4);
;                     nvv = o[192 + rq * 16 + rloc];
;                 }
;                 __builtin_amdgcn_sched_barrier(0);
;                 typedef float f32x2_ __attribute__((ext_vector_type(2)));
;                 f32x2_ ta = (f32x2_){S[0], S[1]} * (f32x2_){a4[0], a4[1]}; ta = (f32x2_){S[2], S[3]} * (f32x2_){a4[2], a4[3]} + ta;
;                 f32x2_ ty = (f32x2_){S[0], S[1]} * (f32x2_){rp[0], rp[1]}; ty = (f32x2_){S[2], S[3]} * (f32x2_){rp[2], rp[3]} + ty;
;                 const f32x4 T = S * d4 + vv * k4;
;                 float sa = ta[0] + ta[1];
;                 float yp = ty[0] + ty[1];
;                 sa = dpp_add<0xB1>(sa); yp = dpp_add<0xB1>(yp);
;                 sa = dpp_add<0x4E>(sa); yp = dpp_add<0x4E>(yp);
;                 sa = dpp_add<0x124>(sa); yp = dpp_add<0x124>(yp);
;                 sa = dpp_add<0x128>(sa); yp = dpp_add<0x128>(yp);
;                 if (tk > 0) yk[(tk - 1) >> 4] = (cg_ == ((tk - 1) & 15)) ? yp : yk[(tk - 1) >> 4];
;                 S = sa * b4 + T;
.LBB0_335:
	s_or_b64 exec, exec, s[74:75]
	s_cmpk_eq_i32 s0, 0x7e0
	s_cbranch_scc1 .Lp3s_nobar
	s_waitcnt lgkmcnt(0)
	s_barrier
.Lp3s_nobar:
	s_add_i32 s73, s73, 1
	s_add_i32 s0, s0, 32
	s_cmpk_eq_i32 s0, 0x800
	s_cbranch_scc1 .LBB0_358

; __device__ __forceinline__ void rwkv_sample_task(const Params& p, int s, int h) {
;     unsigned char* ws = p.ws;
;     const int lane = threadIdx.x & 63, rr = lane >> 4, cg_ = lane & 15;
;     const int row = MP + s;
;     const h16* ob = (const h16*)(ws + OFF_OPS16) + ((size_t)row * 8 + h) * 6 * 64;
;     f32x4 r4, d4, k4, a4, b4;
;     {
;         const h16x4 hr = *(const h16x4*)(ob + cg_ * 4), hw = *(const h16x4*)(ob + 64 + cg_ * 4), hk = *(const h16x4*)(ob + 128 + cg_ * 4),
;                     ha = *(const h16x4*)(ob + 256 + cg_ * 4), hb = *(const h16x4*)(ob + 320 + cg_ * 4);
; #pragma unroll
;         for (int j = 0; j < 4; ++j) { r4[j] = (float)hr[j]; d4[j] = __expf((float)hw[j]); k4[j] = (float)hk[j]; a4[j] = (float)ha[j]; b4[j] = (float)hb[j]; }
;     }
;     const float rk = ((const float*)(ws + OFF_RKS))[(size_t)row * 8 + h];
;     const float* S0 = p.in[6] + ((size_t)s * 8 + h) * 4096;
; __device__ __forceinline__ void p3_scan(const Params& p, LAS unsigned char* lds) {
;     ...
;     const int wave = threadIdx.x >> 6;
;     for (int i = blockIdx.x * 8 + wave; i < MS * 8; i += gridDim.x * 8) rwkv_sample_task(p, i >> 3, i & 7);
.LBB0_360:
	s_movk_i32 s0, 0x400
	v_and_b32_e32 v0, 7, v130
	v_lshrrev_b32_e32 v2, 3, v130
	v_subrev_u32_e32 v3, 4, v0
	v_lshl_add_u32 v2, v2, 2, v3
	v_cmp_lt_u32_e32 vcc, 3, v0
	s_cmpk_eq_i32 s33, 0x100
	s_cselect_b64 s[98:99], -1, 0
	v_mov_b32_e32 v3, 0x7fff0000
	v_cndmask_b32_e32 v143, v3, v2, vcc
	v_cndmask_b32_e64 v143, v130, v143, s[98:99]
	v_cmp_gt_i32_e32 vcc, s0, v143
	s_and_saveexec_b64 s[38:39], vcc
	v_readlane_b32 s48, v253, 20
	v_readlane_b32 s49, v253, 21
	v_readlane_b32 s50, v253, 22
	v_readlane_b32 s51, v253, 23
	v_readlane_b32 s60, v253, 32
	v_readlane_b32 s61, v253, 33
	v_readlane_b32 s62, v253, 34
	v_readlane_b32 s63, v253, 35
	v_readlane_b32 s52, v253, 24
	v_readlane_b32 s53, v253, 25
	v_readlane_b32 s54, v253, 26
	v_readlane_b32 s55, v253, 27
	v_readlane_b32 s56, v253, 28
	v_readlane_b32 s57, v253, 29
	v_readlane_b32 s58, v253, 30
	v_readlane_b32 s59, v253, 31
	s_cbranch_execz .LBB0_363
	s_waitcnt vmcnt(5)
	v_mbcnt_hi_u32_b32 v1, -1, v225
	v_and_b32_e32 v3, 64, v1
	v_add_u32_e32 v3, 64, v3
	s_waitcnt vmcnt(4)
	v_xor_b32_e32 v5, 1, v1
	v_cmp_lt_i32_e64 s[0:1], v5, v3
	v_and_b32_e32 v54, 7, v143
	v_mov_b32_e32 v53, 0
	v_cndmask_b32_e64 v5, v1, v5, s[0:1]
	v_lshlrev_b32_e32 v55, 2, v5
	v_xor_b32_e32 v5, 2, v1
	v_cmp_lt_i32_e64 s[0:1], v5, v3
	v_lshlrev_b32_e32 v0, 6, v144
	v_or_b32_e32 v30, 60, v146
	v_cndmask_b32_e64 v5, v1, v5, s[0:1]
	v_lshlrev_b32_e32 v57, 2, v5
	v_xor_b32_e32 v5, 4, v1
	v_cmp_lt_i32_e64 s[0:1], v5, v3
	v_lshl_add_u64 v[34:35], s[62:63], 0, v[52:53]
	v_or_b32_e32 v2, 0x100, v0
	v_cndmask_b32_e64 v5, v1, v5, s[0:1]
	v_lshlrev_b32_e32 v129, 2, v5
	v_xor_b32_e32 v5, 8, v1
	v_cmp_lt_i32_e64 s[0:1], v5, v3
	v_or_b32_e32 v4, 0x200, v0
	v_or_b32_e32 v6, 0x300, v0
	v_cndmask_b32_e64 v5, v1, v5, s[0:1]
	v_lshlrev_b32_e32 v135, 2, v5
	v_xor_b32_e32 v5, 16, v1
	v_cmp_lt_i32_e64 s[0:1], v5, v3
	s_waitcnt vmcnt(3)
	v_or_b32_e32 v8, 0x400, v0
	v_or_b32_e32 v10, 0x500, v0
	v_cndmask_b32_e64 v5, v1, v5, s[0:1]
	v_lshlrev_b32_e32 v137, 2, v5
	v_xor_b32_e32 v5, 32, v1
	v_cmp_lt_i32_e64 s[0:1], v5, v3
	s_waitcnt vmcnt(2)
	v_or_b32_e32 v12, 0x600, v0
	v_or_b32_e32 v14, 0x700, v0
	v_cndmask_b32_e64 v1, v1, v5, s[0:1]
	v_lshlrev_b32_e32 v139, 2, v1
	v_lshlrev_b32_e32 v1, 6, v54
	s_mov_b64 s[0:1], s[76:77]
	v_readlane_b32 s64, v253, 4
	v_or3_b32 v1, v1, v36, v144
	v_readlane_b32 s76, v253, 16
	v_readlane_b32 s77, v253, 17
	s_waitcnt vmcnt(1)
	v_or_b32_e32 v16, 0x800, v0
	v_or_b32_e32 v18, 0x900, v0
	v_lshl_add_u64 v[58:59], s[76:77], 0, v[52:53]
	s_mov_b64 s[76:77], s[0:1]
	s_mov_b64 s[0:1], 0x546b100
	v_lshlrev_b32_e32 v52, 1, v1
	s_waitcnt vmcnt(0)
	v_or_b32_e32 v20, 0xa00, v0
	v_or_b32_e32 v22, 0xb00, v0
	v_or_b32_e32 v24, 0xc00, v0
	v_or_b32_e32 v26, 0xd00, v0
	v_or_b32_e32 v28, 0xe00, v0
	v_lshlrev_b32_e32 v32, 6, v30
	s_add_u32 s40, s82, 0x1aec800
	v_lshl_add_u64 v[60:61], v[34:35], 0, s[0:1]
	v_lshl_add_u64 v[62:63], s[62:63], 0, v[52:53]
	s_mov_b64 s[0:1], 0x2080000
	v_lshlrev_b32_e32 v52, 2, v1
	v_cmp_eq_u32_e32 vcc, 0, v131
	v_cmp_eq_u32_e64 s[4:5], 1, v131
	v_cmp_eq_u32_e64 s[6:7], 2, v131
	s_movk_i32 s3, 0x300
	v_cmp_eq_u32_e64 s[8:9], 3, v131
	v_cmp_eq_u32_e64 s[10:11], 4, v131
	v_cmp_eq_u32_e64 s[12:13], 5, v131
	v_cmp_eq_u32_e64 s[14:15], 6, v131
	v_cmp_eq_u32_e64 s[16:17], 7, v131
	v_cmp_eq_u32_e64 s[18:19], 8, v131
	v_cmp_eq_u32_e64 s[20:21], 9, v131
	v_cmp_eq_u32_e64 s[22:23], 10, v131
	v_cmp_eq_u32_e64 s[24:25], 11, v131
	v_cmp_eq_u32_e64 s[26:27], 12, v131
	v_cmp_eq_u32_e64 s[28:29], 13, v131
	v_cmp_eq_u32_e64 s[30:31], 14, v131
	v_cmp_eq_u32_e64 s[34:35], 15, v131
	v_lshlrev_b32_e32 v56, 12, v54
	s_addc_u32 s41, s83, 0
	v_lshl_add_u64 v[64:65], v[62:63], 0, s[0:1]
	v_lshl_add_u64 v[66:67], s[48:49], 0, v[52:53]
	v_lshl_add_u64 v[68:69], s[50:51], 0, v[52:53]
	s_mov_b64 s[42:43], 0
	v_lshlrev_b32_e32 v52, 1, v36
	v_lshlrev_b32_e32 v70, 1, v144
	v_lshlrev_b32_e32 v72, 2, v0
	v_lshlrev_b32_e32 v74, 2, v2
	v_lshlrev_b32_e32 v76, 2, v4
	v_lshlrev_b32_e32 v78, 2, v6
	v_lshlrev_b32_e32 v80, 2, v8
	v_lshlrev_b32_e32 v82, 2, v10
	v_lshlrev_b32_e32 v84, 2, v12
	v_lshlrev_b32_e32 v86, 2, v14
	v_lshlrev_b32_e32 v88, 2, v16
	v_lshlrev_b32_e32 v90, 2, v18
	v_lshlrev_b32_e32 v92, 2, v20
	v_lshlrev_b32_e32 v94, 2, v22
	v_lshlrev_b32_e32 v96, 2, v24
	v_lshlrev_b32_e32 v98, 2, v26
	v_lshlrev_b32_e32 v100, 2, v28
	v_lshlrev_b32_e32 v102, 1, v30
	v_lshlrev_b32_e32 v104, 2, v32
	v_mov_b32_e32 v141, 0x3a27c5ac
	s_mov_b32 s44, 0x800000
	s_movk_i32 s45, 0x3ff
	s_nop 0
	v_readlane_b32 s65, v253, 5
	v_readlane_b32 s66, v253, 6
	v_readlane_b32 s67, v253, 7
	v_readlane_b32 s68, v253, 8
	v_readlane_b32 s69, v253, 9
	v_readlane_b32 s70, v253, 10
	v_readlane_b32 s71, v253, 11
	v_readlane_b32 s72, v253, 12
	v_readlane_b32 s73, v253, 13
	v_readlane_b32 s74, v253, 14
	v_readlane_b32 s75, v253, 15
	v_readlane_b32 s78, v253, 18
	v_readlane_b32 s79, v253, 19
